# up-GEMM epilogue stores write-through (sc1) so the grid-barrier L2 write-back is shorter
# speedup vs baseline: 1.0024x; 1.0024x over previous
; template <int EPI>
; DEVI void phase_gemm(const Params& p, const bf16* A, int lda, const bf16* Bt, int K, int NT, bf16* dst, int ldd, char* smem, bool nostore = false,
;                      const float* lng = nullptr, const float* lnb = nullptr) {
;     ...
; #pragma unroll
;       for (int m = 0; m < 4; ++m)
; #pragma unroll
;         for (int n = 0; n < 4; ++n)
; #pragma unroll
;           for (int j = 0; j < 4; ++j) { float v = fmaxf(acc[m][n][j], 0.f); acc[m][n][j] = v * v; }
.LBB0_1861:
	v_max_f32_e32 v0, v62, v62
	v_max_f32_e32 v0, 0, v0
	v_mul_f32_e32 v62, v0, v0
	v_max_f32_e32 v0, v63, v63
	v_max_f32_e32 v0, 0, v0
	v_mul_f32_e32 v63, v0, v0
	v_max_f32_e32 v0, v64, v64
	v_max_f32_e32 v0, 0, v0
	v_mul_f32_e32 v64, v0, v0
	v_max_f32_e32 v0, v65, v65
	v_max_f32_e32 v0, 0, v0
	v_mul_f32_e32 v65, v0, v0
	v_max_f32_e32 v0, v58, v58
	v_max_f32_e32 v0, 0, v0
	v_mul_f32_e32 v58, v0, v0
	v_max_f32_e32 v0, v59, v59
	v_max_f32_e32 v0, 0, v0
	v_mul_f32_e32 v59, v0, v0
	v_max_f32_e32 v0, v60, v60
	v_max_f32_e32 v0, 0, v0
	v_mul_f32_e32 v60, v0, v0
	v_max_f32_e32 v0, v61, v61
	v_max_f32_e32 v0, 0, v0
	v_mul_f32_e32 v61, v0, v0
	v_max_f32_e32 v0, v54, v54
	v_max_f32_e32 v0, 0, v0
	v_mul_f32_e32 v54, v0, v0
	v_max_f32_e32 v0, v55, v55
	v_max_f32_e32 v0, 0, v0
	v_mul_f32_e32 v55, v0, v0
	v_max_f32_e32 v0, v56, v56
	v_max_f32_e32 v0, 0, v0
	v_mul_f32_e32 v56, v0, v0
	v_max_f32_e32 v0, v57, v57
	v_max_f32_e32 v0, 0, v0
	v_mul_f32_e32 v57, v0, v0
	v_max_f32_e32 v0, v50, v50
	v_max_f32_e32 v0, 0, v0
	v_mul_f32_e32 v50, v0, v0
	v_max_f32_e32 v0, v51, v51
	v_max_f32_e32 v0, 0, v0
	v_mul_f32_e32 v51, v0, v0
	v_max_f32_e32 v0, v52, v52
	v_max_f32_e32 v0, 0, v0
	v_mul_f32_e32 v52, v0, v0
	v_max_f32_e32 v0, v53, v53
	v_max_f32_e32 v0, 0, v0
	v_mul_f32_e32 v53, v0, v0
	v_max_f32_e32 v0, v46, v46
	v_max_f32_e32 v0, 0, v0
	v_mul_f32_e32 v46, v0, v0
	v_max_f32_e32 v0, v47, v47
	v_max_f32_e32 v0, 0, v0
	v_mul_f32_e32 v47, v0, v0
	v_max_f32_e32 v0, v48, v48
	v_max_f32_e32 v0, 0, v0
	v_mul_f32_e32 v48, v0, v0
	v_max_f32_e32 v0, v49, v49
	v_max_f32_e32 v0, 0, v0
	v_mul_f32_e32 v49, v0, v0
	v_max_f32_e32 v0, v42, v42
	v_max_f32_e32 v0, 0, v0
	v_mul_f32_e32 v42, v0, v0
	v_max_f32_e32 v0, v43, v43
	v_max_f32_e32 v0, 0, v0
	v_mul_f32_e32 v43, v0, v0
	v_max_f32_e32 v0, v44, v44
	v_max_f32_e32 v0, 0, v0
	v_mul_f32_e32 v44, v0, v0
	v_max_f32_e32 v0, v45, v45
	v_max_f32_e32 v0, 0, v0
	v_mul_f32_e32 v45, v0, v0
	v_max_f32_e32 v0, v38, v38
	v_max_f32_e32 v0, 0, v0
	v_mul_f32_e32 v38, v0, v0
	v_max_f32_e32 v0, v39, v39
	v_max_f32_e32 v0, 0, v0
	v_mul_f32_e32 v39, v0, v0
	v_max_f32_e32 v0, v40, v40
	v_max_f32_e32 v0, 0, v0
	v_mul_f32_e32 v40, v0, v0
	v_max_f32_e32 v0, v41, v41
	v_max_f32_e32 v0, 0, v0
	v_mul_f32_e32 v41, v0, v0
	v_max_f32_e32 v0, v34, v34
	v_max_f32_e32 v0, 0, v0
	v_mul_f32_e32 v34, v0, v0
	v_max_f32_e32 v0, v35, v35
	v_max_f32_e32 v0, 0, v0
	v_mul_f32_e32 v35, v0, v0
	v_max_f32_e32 v0, v36, v36
	v_max_f32_e32 v0, 0, v0
	v_mul_f32_e32 v36, v0, v0
	v_max_f32_e32 v0, v37, v37
	v_max_f32_e32 v0, 0, v0
	v_mul_f32_e32 v37, v0, v0
	v_max_f32_e32 v0, v30, v30
	v_max_f32_e32 v0, 0, v0
	v_mul_f32_e32 v30, v0, v0
	v_max_f32_e32 v0, v31, v31
	v_max_f32_e32 v0, 0, v0
	v_mul_f32_e32 v31, v0, v0
	v_max_f32_e32 v0, v32, v32
	v_max_f32_e32 v0, 0, v0
	v_mul_f32_e32 v32, v0, v0
	v_max_f32_e32 v0, v33, v33
	v_max_f32_e32 v0, 0, v0
	v_mul_f32_e32 v33, v0, v0
	v_max_f32_e32 v0, v26, v26
	v_max_f32_e32 v0, 0, v0
	v_mul_f32_e32 v26, v0, v0
	v_max_f32_e32 v0, v27, v27
	v_max_f32_e32 v0, 0, v0
	v_mul_f32_e32 v27, v0, v0
	v_max_f32_e32 v0, v28, v28
	v_max_f32_e32 v0, 0, v0
	v_mul_f32_e32 v28, v0, v0
	v_max_f32_e32 v0, v29, v29
	v_max_f32_e32 v0, 0, v0
	v_mul_f32_e32 v29, v0, v0
	v_max_f32_e32 v0, v22, v22
	v_max_f32_e32 v0, 0, v0
	v_mul_f32_e32 v22, v0, v0
	v_max_f32_e32 v0, v23, v23
	v_max_f32_e32 v0, 0, v0
	v_mul_f32_e32 v23, v0, v0
	v_max_f32_e32 v0, v24, v24
	v_max_f32_e32 v0, 0, v0
	v_mul_f32_e32 v24, v0, v0
	v_max_f32_e32 v0, v25, v25
	v_max_f32_e32 v0, 0, v0
	v_mul_f32_e32 v25, v0, v0
	v_max_f32_e32 v0, v18, v18
	v_max_f32_e32 v0, 0, v0
	v_mul_f32_e32 v18, v0, v0
	v_max_f32_e32 v0, v19, v19
	v_max_f32_e32 v0, 0, v0
	v_mul_f32_e32 v19, v0, v0
	v_max_f32_e32 v0, v20, v20
	v_max_f32_e32 v0, 0, v0
	v_mul_f32_e32 v20, v0, v0
	v_max_f32_e32 v0, v21, v21
	v_max_f32_e32 v0, 0, v0
	v_mul_f32_e32 v21, v0, v0
	v_max_f32_e32 v0, v14, v14
	v_max_f32_e32 v0, 0, v0
	v_mul_f32_e32 v14, v0, v0
	v_max_f32_e32 v0, v15, v15
	v_max_f32_e32 v0, 0, v0
	v_mul_f32_e32 v15, v0, v0
	v_max_f32_e32 v0, v16, v16
	v_max_f32_e32 v0, 0, v0
	v_mul_f32_e32 v16, v0, v0
	v_max_f32_e32 v0, v17, v17
	v_max_f32_e32 v0, 0, v0
	v_mul_f32_e32 v17, v0, v0
	v_max_f32_e32 v0, v10, v10
; DEVI int opaque_tid() { int t = __builtin_amdgcn_workitem_id_x(); asm volatile("" : "+v"(t)); return t; }
; DEVI void store_rm_sw(const f32x4 (&acc)[4][4], bf16* dst, long ld, int m0, int n0) {
;   const int tid = opaque_tid(), lane = tid & 63, wid = tid >> 6, wr = wid >> 1, wc = wid & 1, fr = lane & 15, fq = lane >> 4;
;   const int cofs = (fq & 1) * 16 + (fq & 2) * 4;
; #pragma unroll
;   for (int m = 0; m < 4; ++m) {
;     bf16* rp = dst + (long)(m0 + wr * 64 + m * 16 + fr) * ld + n0 + wc * 64 + cofs;
; #pragma unroll
;     for (int n = 0; n < 4; n += 2) {
;       const unsigned x0 = pack2(acc[m][n][0], acc[m][n][1]), x1 = pack2(acc[m][n][2], acc[m][n][3]);
;       const unsigned y0 = pack2(acc[m][n + 1][0], acc[m][n + 1][1]), y1 = pack2(acc[m][n + 1][2], acc[m][n + 1][3]);
;       const u32x2 s0 = __builtin_amdgcn_permlane16_swap(x0, y0, false, false);
;       const u32x2 s1 = __builtin_amdgcn_permlane16_swap(x1, y1, false, false);
;       *(u32x4*)(rp + n * 16) = u32x4{s0[0], s1[0], s0[1], s1[1]};
;     }
;   }
; template <int EPI>
; DEVI void phase_gemm(const Params& p, const bf16* A, int lda, const bf16* Bt, int K, int NT, bf16* dst, int ldd, char* smem, bool nostore = false,
;                      const float* lng = nullptr, const float* lnb = nullptr) {
;     ...
;       for (int m = 0; m < 4; ++m)
; #pragma unroll
;         for (int n = 0; n < 4; ++n)
; #pragma unroll
;           for (int j = 0; j < 4; ++j) { float v = fmaxf(acc[m][n][j], 0.f); acc[m][n][j] = v * v; }
;       if (!nostore || acc[0][0][0] == 123.456f) store_rm_sw(acc, dst, ldd, mt * 128, nt * 128);
	v_max_f32_e32 v0, 0, v0
	v_mul_f32_e32 v66, v0, v0
	v_max_f32_e32 v0, v11, v11
	v_max_f32_e32 v0, 0, v0
	v_mul_f32_e32 v67, v0, v0
	v_max_f32_e32 v0, v12, v12
	v_max_f32_e32 v0, 0, v0
	v_mul_f32_e32 v12, v0, v0
	v_max_f32_e32 v0, v13, v13
	v_max_f32_e32 v0, 0, v0
	v_mul_f32_e32 v13, v0, v0
	v_max_f32_e32 v0, v6, v6
	v_max_f32_e32 v0, 0, v0
	v_mul_f32_e32 v68, v0, v0
	v_max_f32_e32 v0, v7, v7
	v_max_f32_e32 v0, 0, v0
	v_mul_f32_e32 v69, v0, v0
	v_max_f32_e32 v0, v8, v8
	v_max_f32_e32 v0, 0, v0
	v_mul_f32_e32 v70, v0, v0
	v_max_f32_e32 v0, v9, v9
	v_max_f32_e32 v0, 0, v0
	v_mul_f32_e32 v71, v0, v0
	v_max_f32_e32 v0, v2, v2
	v_max_f32_e32 v0, 0, v0
	v_mul_f32_e32 v72, v0, v0
	v_max_f32_e32 v0, v3, v3
	v_max_f32_e32 v0, 0, v0
	v_mul_f32_e32 v73, v0, v0
	v_max_f32_e32 v0, v4, v4
	v_max_f32_e32 v0, 0, v0
	s_lshl_b32 s10, s40, 4
	v_mul_f32_e32 v74, v0, v0
	v_max_f32_e32 v0, v5, v5
	s_sub_i32 s10, s10, s41
	v_max_f32_e32 v0, 0, v0
	s_and_b32 s40, s10, 0xffffff80
	v_mul_f32_e32 v75, v0, v0
	v_mov_b32_e32 v0, v154
	s_ashr_i32 s41, s40, 31
	v_and_b32_e32 v3, 16, v0
	v_lshrrev_b32_e32 v4, 2, v0
	v_and_or_b32 v4, v4, 8, v3
	v_ashrrev_i32_e32 v3, 1, v0
	s_lshl_b64 s[40:41], s[40:41], 1
	v_and_b32_e32 v2, 64, v0
	v_and_b32_e32 v3, 0xffffffc0, v3
	v_and_or_b32 v0, v0, 15, s13
	s_add_u32 s40, s14, s40
	v_add_u32_e32 v6, v0, v3
	s_addc_u32 s41, s15, s41
	v_lshlrev_b32_e32 v0, 1, v2
	v_lshl_add_u64 v[2:3], s[40:41], 0, v[0:1]
	v_lshlrev_b32_e32 v0, 1, v4
	v_ashrrev_i32_e32 v7, 31, v6
	v_lshl_add_u64 v[8:9], v[2:3], 0, v[0:1]
	v_lshlrev_b64 v[2:3], 13, v[6:7]
	v_lshl_add_u64 v[10:11], v[8:9], 0, v[2:3]
	v_cvt_pk_bf16_f32 v2, v62, v63
	v_cvt_pk_bf16_f32 v3, v64, v65
	v_cvt_pk_bf16_f32 v4, v58, v59
	v_cvt_pk_bf16_f32 v5, v60, v61
	s_nop 0
	v_permlane16_swap_b32_e32 v2, v4
	v_permlane16_swap_b32_e32 v3, v5
	flat_store_dwordx4 v[10:11], v[2:5] sc1
	v_readlane_b32 s10, v249, 47
	s_andn2_b64 vcc, exec, s[38:39]
	v_cvt_pk_bf16_f32 v2, v54, v55
	v_cvt_pk_bf16_f32 v3, v56, v57
	v_cvt_pk_bf16_f32 v4, v50, v51
	v_cvt_pk_bf16_f32 v5, v52, v53
	s_nop 0
	v_permlane16_swap_b32_e32 v2, v4
	v_permlane16_swap_b32_e32 v3, v5
	flat_store_dwordx4 v[10:11], v[2:5] offset:64 sc1
	s_add_i32 s6, s6, s10
	s_nop 0
	v_or_b32_e32 v2, 16, v6
	v_ashrrev_i32_e32 v3, 31, v2
	v_lshlrev_b64 v[2:3], 13, v[2:3]
	v_lshl_add_u64 v[10:11], v[8:9], 0, v[2:3]
	v_cvt_pk_bf16_f32 v2, v46, v47
	v_cvt_pk_bf16_f32 v3, v48, v49
	v_cvt_pk_bf16_f32 v4, v42, v43
	v_cvt_pk_bf16_f32 v5, v44, v45
	s_nop 0
	v_permlane16_swap_b32_e32 v2, v4
	v_permlane16_swap_b32_e32 v3, v5
	flat_store_dwordx4 v[10:11], v[2:5] sc1
	s_nop 1
	v_cvt_pk_bf16_f32 v2, v38, v39
	v_cvt_pk_bf16_f32 v3, v40, v41
	v_cvt_pk_bf16_f32 v4, v34, v35
	v_cvt_pk_bf16_f32 v5, v36, v37
	s_nop 0
	v_permlane16_swap_b32_e32 v2, v4
	v_permlane16_swap_b32_e32 v3, v5
	flat_store_dwordx4 v[10:11], v[2:5] offset:64 sc1
	s_nop 1
	v_or_b32_e32 v2, 32, v6
	v_ashrrev_i32_e32 v3, 31, v2
	v_lshlrev_b64 v[2:3], 13, v[2:3]
	v_lshl_add_u64 v[10:11], v[8:9], 0, v[2:3]
	v_cvt_pk_bf16_f32 v2, v30, v31
	v_cvt_pk_bf16_f32 v3, v32, v33
	v_cvt_pk_bf16_f32 v4, v26, v27
	v_cvt_pk_bf16_f32 v5, v28, v29
	s_nop 0
	v_permlane16_swap_b32_e32 v2, v4
	v_permlane16_swap_b32_e32 v3, v5
	flat_store_dwordx4 v[10:11], v[2:5] sc1
	s_nop 1
	v_cvt_pk_bf16_f32 v2, v22, v23
	v_cvt_pk_bf16_f32 v3, v24, v25
	v_cvt_pk_bf16_f32 v4, v18, v19
	v_cvt_pk_bf16_f32 v5, v20, v21
	s_nop 0
	v_permlane16_swap_b32_e32 v2, v4
	v_permlane16_swap_b32_e32 v3, v5
	flat_store_dwordx4 v[10:11], v[2:5] offset:64 sc1
	s_nop 1
	v_or_b32_e32 v2, 48, v6
	v_ashrrev_i32_e32 v3, 31, v2
	v_lshlrev_b64 v[2:3], 13, v[2:3]
	v_lshl_add_u64 v[6:7], v[8:9], 0, v[2:3]
	v_cvt_pk_bf16_f32 v2, v14, v15
	v_cvt_pk_bf16_f32 v3, v16, v17
	v_cvt_pk_bf16_f32 v4, v66, v67
	v_cvt_pk_bf16_f32 v5, v12, v13
	s_nop 0
	v_permlane16_swap_b32_e32 v2, v4
	v_permlane16_swap_b32_e32 v3, v5
	flat_store_dwordx4 v[6:7], v[2:5] sc1
	s_nop 1
	v_cvt_pk_bf16_f32 v2, v68, v69
	v_cvt_pk_bf16_f32 v3, v70, v71
	v_cvt_pk_bf16_f32 v4, v72, v73
	v_cvt_pk_bf16_f32 v5, v74, v75
	s_nop 0
	v_permlane16_swap_b32_e32 v2, v4
	v_permlane16_swap_b32_e32 v3, v5
	flat_store_dwordx4 v[6:7], v[2:5] offset:64 sc1
	s_cbranch_vccz .LBB0_1866
